# grid barrier release made single-hop (last XCD leader bumps all per-XCD release words)
# speedup vs baseline: 1.0304x; 1.0001x over previous
; #define RUN_PHASE(k, fn)                                  \
;   if (ph_lo <= k && k <= ph_hi) {                         \
;     if (k == PROBE_DUP) { fn(p, smem); cg::this_grid().sync(); } \
;     fn(p, smem);                                          \
;     if (k < ph_hi) cg::this_grid().sync();                \
;   }
; __global__ void __launch_bounds__(512) mega(Params p, int ph_lo, int ph_hi) {
;     ...
;   RUN_PHASE(1, phase1)
.Lgb0_census_ok:
	s_mov_b32 s98, s12
	s_cmp_eq_u32 s100, 1
	s_cselect_b32 s98, s13, s98
	s_cmp_eq_u32 s100, 2
	s_cselect_b32 s98, s14, s98
	s_cmp_eq_u32 s100, 3
	s_cselect_b32 s98, s15, s98
	s_cmp_eq_u32 s100, 4
	s_cselect_b32 s98, s16, s98
	s_cmp_eq_u32 s100, 5
	s_cselect_b32 s98, s17, s98
	s_cmp_eq_u32 s100, 6
	s_cselect_b32 s98, s18, s98
	s_cmp_eq_u32 s100, 7
	s_cselect_b32 s98, s19, s98
	s_max_u32 s98, s98, 1
	s_max_u32 s99, s21, 1
	s_lshl_b32 s0, s100, 8
	s_add_i32 s1, s0, 0x1000
	v_mov_b32_e32 v1, s1
	global_atomic_add v2, v1, v11, s[8:9] sc0
	s_add_i32 s2, s0, 0x2000
	s_mul_i32 s3, s98, 1
	s_mul_i32 s6, s99, 1
	s_waitcnt vmcnt(0)
	v_readfirstlane_b32 s7, v2
	s_add_i32 s7, s7, 1
	s_cmp_eq_u32 s7, s3
	s_cbranch_scc0 .Lgb0_wait
	buffer_wbl2 sc1
	s_waitcnt vmcnt(0)
	v_mov_b32_e32 v1, 0x3000
	global_atomic_add v2, v1, v11, s[8:9] sc0
	s_waitcnt vmcnt(0)
	v_readfirstlane_b32 s7, v2
	s_add_i32 s7, s7, 1
	v_mov_b32_e32 v1, 0x3100
	s_cmp_eq_u32 s7, s6
	s_cbranch_scc0 .Lgb0_wait
	v_mov_b32_e32 v12, 0x2000
	global_atomic_add v12, v11, s[8:9]
	global_atomic_add v12, v11, s[8:9] offset:256
	global_atomic_add v12, v11, s[8:9] offset:512
	global_atomic_add v12, v11, s[8:9] offset:768
	global_atomic_add v12, v11, s[8:9] offset:1024
	global_atomic_add v12, v11, s[8:9] offset:1280
	global_atomic_add v12, v11, s[8:9] offset:1536
	global_atomic_add v12, v11, s[8:9] offset:1792

; #define RUN_PHASE(k, fn)                                  \
;   if (ph_lo <= k && k <= ph_hi) {                         \
;     if (k == PROBE_DUP) { fn(p, smem); cg::this_grid().sync(); } \
;     fn(p, smem);                                          \
;     if (k < ph_hi) cg::this_grid().sync();                \
;   }
; __global__ void __launch_bounds__(512) mega(Params p, int ph_lo, int ph_hi) {
;     ...
;   RUN_PHASE(2, phase2)
.LBB0_596:
	s_cmp_lt_i32 s91, 3
	s_cbranch_scc1 .LBB0_608
	s_waitcnt vmcnt(0) lgkmcnt(0)
	s_barrier
	v_cmp_eq_u32_e32 vcc, 0, v0
	s_and_saveexec_b64 s[4:5], vcc
	s_cbranch_execz .Lgb1_done
	s_add_u32 s8, s88, 0xb20000
	s_addc_u32 s9, s89, 0
	v_mov_b32_e32 v10, 0
	v_mov_b32_e32 v11, 1
	s_lshl_b32 s0, s100, 8
	s_add_i32 s1, s0, 0x1000
	v_mov_b32_e32 v1, s1
	global_atomic_add v2, v1, v11, s[8:9] sc0
	s_add_i32 s2, s0, 0x2000
	s_mul_i32 s3, s98, 2
	s_mul_i32 s6, s99, 2
	s_waitcnt vmcnt(0)
	v_readfirstlane_b32 s7, v2
	s_add_i32 s7, s7, 1
	s_cmp_eq_u32 s7, s3
	s_cbranch_scc0 .Lgb1_wait
	buffer_wbl2 sc1
	s_waitcnt vmcnt(0)
	v_mov_b32_e32 v1, 0x3000
	global_atomic_add v2, v1, v11, s[8:9] sc0
	s_waitcnt vmcnt(0)
	v_readfirstlane_b32 s7, v2
	s_add_i32 s7, s7, 1
	v_mov_b32_e32 v1, 0x3100
	s_cmp_eq_u32 s7, s6
	s_cbranch_scc0 .Lgb1_wait
	v_mov_b32_e32 v12, 0x2000
	global_atomic_add v12, v11, s[8:9]
	global_atomic_add v12, v11, s[8:9] offset:256
	global_atomic_add v12, v11, s[8:9] offset:512
	global_atomic_add v12, v11, s[8:9] offset:768
	global_atomic_add v12, v11, s[8:9] offset:1024
	global_atomic_add v12, v11, s[8:9] offset:1280
	global_atomic_add v12, v11, s[8:9] offset:1536
	global_atomic_add v12, v11, s[8:9] offset:1792

; #define RUN_PHASE(k, fn)                                  \
;   if (ph_lo <= k && k <= ph_hi) {                         \
;     if (k == PROBE_DUP) { fn(p, smem); cg::this_grid().sync(); } \
;     fn(p, smem);                                          \
;     if (k < ph_hi) cg::this_grid().sync();                \
;   }
; __global__ void __launch_bounds__(512) mega(Params p, int ph_lo, int ph_hi) {
;     ...
;   RUN_PHASE(3, phase3)
.LBB0_664:
	s_cmp_lt_i32 s91, 4
	s_cbranch_scc1 .LBB0_676
	s_waitcnt vmcnt(0) lgkmcnt(0)
	s_barrier
	v_cmp_eq_u32_e32 vcc, 0, v0
	s_and_saveexec_b64 s[4:5], vcc
	s_cbranch_execz .Lgb2_done
	s_add_u32 s8, s88, 0xb20000
	s_addc_u32 s9, s89, 0
	v_mov_b32_e32 v10, 0
	v_mov_b32_e32 v11, 1
	s_lshl_b32 s0, s100, 8
	s_add_i32 s1, s0, 0x1000
	v_mov_b32_e32 v1, s1
	global_atomic_add v2, v1, v11, s[8:9] sc0
	s_add_i32 s2, s0, 0x2000
	s_mul_i32 s3, s98, 3
	s_mul_i32 s6, s99, 3
	s_waitcnt vmcnt(0)
	v_readfirstlane_b32 s7, v2
	s_add_i32 s7, s7, 1
	s_cmp_eq_u32 s7, s3
	s_cbranch_scc0 .Lgb2_wait
	buffer_wbl2 sc1
	s_waitcnt vmcnt(0)
	v_mov_b32_e32 v1, 0x3000
	global_atomic_add v2, v1, v11, s[8:9] sc0
	s_waitcnt vmcnt(0)
	v_readfirstlane_b32 s7, v2
	s_add_i32 s7, s7, 1
	v_mov_b32_e32 v1, 0x3100
	s_cmp_eq_u32 s7, s6
	s_cbranch_scc0 .Lgb2_wait
	v_mov_b32_e32 v12, 0x2000
	global_atomic_add v12, v11, s[8:9]
	global_atomic_add v12, v11, s[8:9] offset:256
	global_atomic_add v12, v11, s[8:9] offset:512
	global_atomic_add v12, v11, s[8:9] offset:768
	global_atomic_add v12, v11, s[8:9] offset:1024
	global_atomic_add v12, v11, s[8:9] offset:1280
	global_atomic_add v12, v11, s[8:9] offset:1536
	global_atomic_add v12, v11, s[8:9] offset:1792

; #define RUN_PHASE(k, fn)                                  \
;   if (ph_lo <= k && k <= ph_hi) {                         \
;     if (k == PROBE_DUP) { fn(p, smem); cg::this_grid().sync(); } \
;     fn(p, smem);                                          \
;     if (k < ph_hi) cg::this_grid().sync();                \
;   }
; __global__ void __launch_bounds__(512) mega(Params p, int ph_lo, int ph_hi) {
;     ...
;   RUN_PHASE(4, phase4)
.LBB0_718:
	s_cmp_lt_i32 s91, 5
	s_cbranch_scc1 .LBB0_730
	s_waitcnt vmcnt(0) lgkmcnt(0)
	s_barrier
	v_cmp_eq_u32_e32 vcc, 0, v0
	s_and_saveexec_b64 s[4:5], vcc
	s_cbranch_execz .Lgb3_done
	s_add_u32 s8, s88, 0xb20000
	s_addc_u32 s9, s89, 0
	v_mov_b32_e32 v10, 0
	v_mov_b32_e32 v11, 1
	s_lshl_b32 s0, s100, 8
	s_add_i32 s1, s0, 0x1000
	v_mov_b32_e32 v1, s1
	global_atomic_add v2, v1, v11, s[8:9] sc0
	s_add_i32 s2, s0, 0x2000
	s_mul_i32 s3, s98, 4
	s_mul_i32 s6, s99, 4
	s_waitcnt vmcnt(0)
	v_readfirstlane_b32 s7, v2
	s_add_i32 s7, s7, 1
	s_cmp_eq_u32 s7, s3
	s_cbranch_scc0 .Lgb3_wait
	buffer_wbl2 sc1
	s_waitcnt vmcnt(0)
	v_mov_b32_e32 v1, 0x3000
	global_atomic_add v2, v1, v11, s[8:9] sc0
	s_waitcnt vmcnt(0)
	v_readfirstlane_b32 s7, v2
	s_add_i32 s7, s7, 1
	v_mov_b32_e32 v1, 0x3100
	s_cmp_eq_u32 s7, s6
	s_cbranch_scc0 .Lgb3_wait
	v_mov_b32_e32 v12, 0x2000
	global_atomic_add v12, v11, s[8:9]
	global_atomic_add v12, v11, s[8:9] offset:256
	global_atomic_add v12, v11, s[8:9] offset:512
	global_atomic_add v12, v11, s[8:9] offset:768
	global_atomic_add v12, v11, s[8:9] offset:1024
	global_atomic_add v12, v11, s[8:9] offset:1280
	global_atomic_add v12, v11, s[8:9] offset:1536
	global_atomic_add v12, v11, s[8:9] offset:1792

; #define RUN_PHASE(k, fn)                                  \
;   if (ph_lo <= k && k <= ph_hi) {                         \
;     if (k == PROBE_DUP) { fn(p, smem); cg::this_grid().sync(); } \
;     fn(p, smem);                                          \
;     if (k < ph_hi) cg::this_grid().sync();                \
;   }
; __global__ void __launch_bounds__(512) mega(Params p, int ph_lo, int ph_hi) {
;     ...
;   RUN_PHASE(5, phase5)
.LBB0_770:
	s_cmp_lt_i32 s91, 6
	s_cbranch_scc1 .LBB0_782
	s_waitcnt vmcnt(0) lgkmcnt(0)
	s_barrier
	v_cmp_eq_u32_e32 vcc, 0, v0
	s_and_saveexec_b64 s[4:5], vcc
	s_cbranch_execz .Lgb4_done
	s_add_u32 s8, s88, 0xb20000
	s_addc_u32 s9, s89, 0
	v_mov_b32_e32 v10, 0
	v_mov_b32_e32 v11, 1
	s_lshl_b32 s0, s100, 8
	s_add_i32 s1, s0, 0x1000
	v_mov_b32_e32 v1, s1
	global_atomic_add v2, v1, v11, s[8:9] sc0
	s_add_i32 s2, s0, 0x2000
	s_mul_i32 s3, s98, 5
	s_mul_i32 s6, s99, 5
	s_waitcnt vmcnt(0)
	v_readfirstlane_b32 s7, v2
	s_add_i32 s7, s7, 1
	s_cmp_eq_u32 s7, s3
	s_cbranch_scc0 .Lgb4_wait
	buffer_wbl2 sc1
	s_waitcnt vmcnt(0)
	v_mov_b32_e32 v1, 0x3000
	global_atomic_add v2, v1, v11, s[8:9] sc0
	s_waitcnt vmcnt(0)
	v_readfirstlane_b32 s7, v2
	s_add_i32 s7, s7, 1
	v_mov_b32_e32 v1, 0x3100
	s_cmp_eq_u32 s7, s6
	s_cbranch_scc0 .Lgb4_wait
	v_mov_b32_e32 v12, 0x2000
	global_atomic_add v12, v11, s[8:9]
	global_atomic_add v12, v11, s[8:9] offset:256
	global_atomic_add v12, v11, s[8:9] offset:512
	global_atomic_add v12, v11, s[8:9] offset:768
	global_atomic_add v12, v11, s[8:9] offset:1024
	global_atomic_add v12, v11, s[8:9] offset:1280
	global_atomic_add v12, v11, s[8:9] offset:1536
	global_atomic_add v12, v11, s[8:9] offset:1792

; #define RUN_PHASE(k, fn)                                  \
;   if (ph_lo <= k && k <= ph_hi) {                         \
;     if (k == PROBE_DUP) { fn(p, smem); cg::this_grid().sync(); } \
;     fn(p, smem);                                          \
;     if (k < ph_hi) cg::this_grid().sync();                \
;   }
; __global__ void __launch_bounds__(512) mega(Params p, int ph_lo, int ph_hi) {
;     ...
;   RUN_PHASE(6, phase6)
.LBB0_805:
	s_cmp_lt_i32 s91, 7
	s_cbranch_scc1 .LBB0_817
	s_waitcnt vmcnt(0) lgkmcnt(0)
	s_barrier
	v_cmp_eq_u32_e32 vcc, 0, v0
	s_and_saveexec_b64 s[4:5], vcc
	s_cbranch_execz .Lgb5_done
	s_add_u32 s8, s88, 0xb20000
	s_addc_u32 s9, s89, 0
	v_mov_b32_e32 v10, 0
	v_mov_b32_e32 v11, 1
	s_lshl_b32 s0, s100, 8
	s_add_i32 s1, s0, 0x1000
	v_mov_b32_e32 v1, s1
	global_atomic_add v2, v1, v11, s[8:9] sc0
	s_add_i32 s2, s0, 0x2000
	s_mul_i32 s3, s98, 6
	s_mul_i32 s6, s99, 6
	s_waitcnt vmcnt(0)
	v_readfirstlane_b32 s7, v2
	s_add_i32 s7, s7, 1
	s_cmp_eq_u32 s7, s3
	s_cbranch_scc0 .Lgb5_wait
	buffer_wbl2 sc1
	s_waitcnt vmcnt(0)
	v_mov_b32_e32 v1, 0x3000
	global_atomic_add v2, v1, v11, s[8:9] sc0
	s_waitcnt vmcnt(0)
	v_readfirstlane_b32 s7, v2
	s_add_i32 s7, s7, 1
	v_mov_b32_e32 v1, 0x3100
	s_cmp_eq_u32 s7, s6
	s_cbranch_scc0 .Lgb5_wait
	v_mov_b32_e32 v12, 0x2000
	global_atomic_add v12, v11, s[8:9]
	global_atomic_add v12, v11, s[8:9] offset:256
	global_atomic_add v12, v11, s[8:9] offset:512
	global_atomic_add v12, v11, s[8:9] offset:768
	global_atomic_add v12, v11, s[8:9] offset:1024
	global_atomic_add v12, v11, s[8:9] offset:1280
	global_atomic_add v12, v11, s[8:9] offset:1536
	global_atomic_add v12, v11, s[8:9] offset:1792

; #define RUN_PHASE(k, fn)                                  \
;   if (ph_lo <= k && k <= ph_hi) {                         \
;     if (k == PROBE_DUP) { fn(p, smem); cg::this_grid().sync(); } \
;     fn(p, smem);                                          \
;     if (k < ph_hi) cg::this_grid().sync();                \
;   }
; __global__ void __launch_bounds__(512) mega(Params p, int ph_lo, int ph_hi) {
;     ...
;   RUN_PHASE(7, phase7)
.LBB0_836:
	s_cmp_lt_i32 s91, 8
	s_cbranch_scc1 .LBB0_848
	s_waitcnt vmcnt(0) lgkmcnt(0)
	s_barrier
	v_cmp_eq_u32_e32 vcc, 0, v0
	s_and_saveexec_b64 s[4:5], vcc
	s_cbranch_execz .Lgb6_done
	s_add_u32 s8, s88, 0xb20000
	s_addc_u32 s9, s89, 0
	v_mov_b32_e32 v10, 0
	v_mov_b32_e32 v11, 1
	s_lshl_b32 s0, s100, 8
	s_add_i32 s1, s0, 0x1000
	v_mov_b32_e32 v1, s1
	global_atomic_add v2, v1, v11, s[8:9] sc0
	s_add_i32 s2, s0, 0x2000
	s_mul_i32 s3, s98, 7
	s_mul_i32 s6, s99, 7
	s_waitcnt vmcnt(0)
	v_readfirstlane_b32 s7, v2
	s_add_i32 s7, s7, 1
	s_cmp_eq_u32 s7, s3
	s_cbranch_scc0 .Lgb6_wait
	buffer_wbl2 sc1
	s_waitcnt vmcnt(0)
	v_mov_b32_e32 v1, 0x3000
	global_atomic_add v2, v1, v11, s[8:9] sc0
	s_waitcnt vmcnt(0)
	v_readfirstlane_b32 s7, v2
	s_add_i32 s7, s7, 1
	v_mov_b32_e32 v1, 0x3100
	s_cmp_eq_u32 s7, s6
	s_cbranch_scc0 .Lgb6_wait
	v_mov_b32_e32 v12, 0x2000
	global_atomic_add v12, v11, s[8:9]
	global_atomic_add v12, v11, s[8:9] offset:256
	global_atomic_add v12, v11, s[8:9] offset:512
	global_atomic_add v12, v11, s[8:9] offset:768
	global_atomic_add v12, v11, s[8:9] offset:1024
	global_atomic_add v12, v11, s[8:9] offset:1280
	global_atomic_add v12, v11, s[8:9] offset:1536
	global_atomic_add v12, v11, s[8:9] offset:1792
